# P12->P13 grid barrier replaced by arrival counter + deferred wait/invalidate in first P13 K loop (P12 stores write-through)
# speedup vs baseline: 1.0101x; 1.0038x over previous
.LBB0_1570:
	s_or_b64 exec, exec, s[10:11]
	s_waitcnt vmcnt(0)
	s_barrier
	s_and_saveexec_b64 s[10:11], s[92:93]
	s_cbranch_execz .LBB0_1622
	v_mov_b32_e32 v2, 0x2b5d00c
	v_mov_b32_e32 v3, 1
	global_atomic_add v2, v3, s[88:89]
.LBB0_1622:
	s_or_b64 exec, exec, s[10:11]
	v_readlane_b32 s0, v254, 11
	s_waitcnt lgkmcnt(0)
	v_mov_b32_e32 v2, v0
	v_mov_b32_e32 v6, v0
	v_readlane_b32 s1, v254, 12
	s_barrier
	s_mov_b32 s100, 1
	s_and_b64 vcc, exec, s[0:1]
	v_readfirstlane_b32 s0, v6
	s_cbranch_vccnz .LBB0_1638
	v_bfe_i32 v3, v6, 27, 1
	v_lshlrev_b32_e32 v2, 4, v6
	v_lshrrev_b32_e32 v3, 22, v3
	v_add_u32_e32 v3, v2, v3
	v_and_b32_e32 v3, 0xfffffc00, v3
	v_sub_u32_e32 v2, v2, v3
	v_lshrrev_b32_e32 v3, 4, v2
	v_ashrrev_i32_e32 v4, 31, v6
	s_load_dwordx4 s[8:11], s[96:97], 0xe0
	v_bitop3_b32 v2, v3, v2, 32 bitop3:0x6c
	v_lshrrev_b32_e32 v4, 26, v4
	v_ashrrev_i32_e32 v3, 31, v2
	v_add_u32_e32 v4, v6, v4
	v_lshrrev_b32_e32 v3, 26, v3
	v_ashrrev_i32_e32 v8, 6, v4
	v_add_u32_e32 v3, v2, v3
	v_lshlrev_b32_e32 v4, 3, v8
	v_ashrrev_i32_e32 v7, 6, v3
	v_and_b32_e32 v4, -16, v4
	s_waitcnt lgkmcnt(0)
	s_add_u32 s3, s10, 0xae00000
	v_add_u32_e32 v4, v7, v4
	v_and_b32_e32 v5, 3, v7
	s_mov_b32 s6, 0x1fffe0
	s_addc_u32 s4, s11, 0
	v_and_or_b32 v5, v4, s6, v5
	s_and_b32 s6, s83, 56
	s_bfe_u32 s7, s2, 0x30005
	s_ashr_i32 s1, s0, 6
	s_or_b32 s6, s6, s7
	s_ashr_i32 s18, s0, 8
	s_lshl_b32 s5, s1, 10
	s_ashr_i32 s31, s2, 8
	s_lshl_b32 s23, s6, 18
	s_lshl_b32 s6, s6, 19
	s_add_u32 s60, s3, s6
	s_addc_u32 s61, s4, 0
	s_lshl_b32 s6, s2, 5
	s_lshl_b32 s22, s31, 10
	s_and_b32 s30, s6, 0x300
	v_lshrrev_b32_e32 v9, 2, v4
	v_lshlrev_b32_e32 v10, 1, v4
	v_and_b32_e32 v3, 0xc0, v3
	s_or_b32 s6, s22, s30
	v_and_b32_e32 v9, 4, v9
	v_and_b32_e32 v10, 24, v10
	v_sub_u32_e32 v2, v2, v3
	v_mov_b32_e32 v3, 1
	s_addk_i32 s6, 0xc00
	v_or3_b32 v5, v5, v9, v10
	v_lshlrev_b32_e32 v9, 5, v8
	v_ashrrev_i16_sdwa v2, v3, sext(v2) dst_sel:DWORD dst_unused:UNUSED_PAD src0_sel:DWORD src1_sel:BYTE_0
	s_ashr_i32 s7, s6, 31
	v_and_b32_e32 v10, 32, v9
	v_bfe_i32 v9, v2, 0, 16
	s_lshl_b64 s[6:7], s[6:7], 11
	v_add_lshl_u32 v2, v10, v9, 1
	s_add_u32 s62, s10, s6
	v_lshl_add_u32 v162, v5, 11, v2
	s_addc_u32 s63, s11, s7
	v_mov_b32_e32 v163, 0
	s_add_i32 s6, s5, 0
	v_lshl_add_u32 v164, v4, 11, v2
	v_lshl_add_u64 v[2:3], s[62:63], 0, v[162:163]
	s_add_i32 m0, s6, 0x10000
	s_mov_b64 s[12:13], 0x20000
	global_load_lds_dwordx4 v162, s[62:63]
	v_lshl_add_u64 v[4:5], v[2:3], 0, s[12:13]
	s_add_i32 m0, s6, 0x12000
	v_mov_b32_e32 v165, v163
	global_load_lds_dwordx4 v[4:5], off
	v_lshl_add_u64 v[4:5], s[60:61], 0, v[164:165]
	s_mov_b32 m0, s6
	s_add_i32 s7, s6, 0x2000
	global_load_lds_dwordx4 v164, s[60:61]
	v_lshl_add_u64 v[10:11], v[4:5], 0, s[12:13]
	s_mov_b32 m0, s7
	s_mov_b64 s[14:15], 0x40000
	global_load_lds_dwordx4 v[10:11], off
	v_lshl_add_u64 v[10:11], v[2:3], 0, s[14:15]
	s_add_i32 m0, s6, 0x14000
	s_mov_b64 s[16:17], 0x60000
	global_load_lds_dwordx4 v[10:11], off
	v_lshl_add_u64 v[10:11], v[2:3], 0, s[16:17]
	s_add_i32 m0, s6, 0x16000
	s_add_i32 s24, s6, 0x4000
	global_load_lds_dwordx4 v[10:11], off
	v_lshl_add_u64 v[10:11], v[4:5], 0, s[14:15]
	s_mov_b32 m0, s24
	s_add_i32 s25, s6, 0x6000
	global_load_lds_dwordx4 v[10:11], off
	v_lshl_add_u64 v[10:11], v[4:5], 0, s[16:17]
	s_mov_b32 m0, s25
	s_cmp_eq_u32 s18, 1
	global_load_lds_dwordx4 v[10:11], off
	s_mov_b32 s19, 0
	s_cselect_b64 s[20:21], -1, 0
	s_cmp_lg_u32 s18, 1
	s_mov_b32 s26, 0x10000
	s_cbranch_scc1 .LBB0_1625
	s_barrier

.LBB0_1631:
	s_cmp_lg_u32 s100, 1
	s_cbranch_scc1 .Ldw_skip_p13
	s_cmp_lg_u32 s79, 8
	s_cbranch_scc1 .Ldw_skip_p13
	s_mov_b32 s100, 0
	s_cmp_eq_u64 s[92:93], 0
	s_cbranch_scc1 .Ldw_skip_p13
	s_mov_b32 s99, 0x2b5d00c
	v_mov_b32_e32 v218, s99
	s_mov_b32 s101, 0x100000
.Ldw_poll_p13:
	global_load_dword v219, v218, s[88:89] sc1
	s_waitcnt vmcnt(0)
	v_readfirstlane_b32 s99, v219
	s_cmp_ge_u32 s99, 0x100
	s_cbranch_scc1 .Ldw_done_p13
	s_sleep 1
	s_sub_u32 s101, s101, 1
	s_cmp_lg_u32 s101, 0
	s_cbranch_scc1 .Ldw_poll_p13
.Ldw_done_p13:
	buffer_inv sc1
.Ldw_skip_p13:
	ds_read_b128 v[122:125], v189
	ds_read_b128 v[134:137], v189 offset:1024
	ds_read_b128 v[138:141], v189 offset:2048
	ds_read_b128 v[142:145], v189 offset:3072
	ds_read_b128 v[192:195], v191
	ds_read_b128 v[196:199], v191 offset:1024
	ds_read_b128 v[200:203], v191 offset:2048
	ds_read_b128 v[204:207], v191 offset:3072
	s_add_u32 s0, s60, 0xfffc0080
	s_addc_u32 s1, s61, -1
	s_cmp_eq_u32 s79, 12
	s_cselect_b32 s1, s57, s1
	s_cselect_b32 s0, s56, s0
	s_cselect_b32 s31, s59, s63
	s_cselect_b32 s30, s58, s62
	v_lshl_add_u64 v[252:253], s[60:61], 0, v[166:167]
	s_add_i32 m0, s6, 0xc000
	ds_read_b128 v[146:149], v190
	ds_read_b128 v[150:153], v190 offset:1024
	ds_read_b128 v[154:157], v190 offset:2048
	ds_read_b128 v[158:161], v190 offset:3072
	ds_read_b128 v[168:171], v190 offset:4096
	ds_read_b128 v[172:175], v190 offset:5120
	ds_read_b128 v[176:179], v190 offset:6144
	ds_read_b128 v[180:183], v190 offset:7168
	global_load_lds_dwordx4 v[252:253], off
	v_lshl_add_u64 v[252:253], v[252:253], 0, s[12:13]
	s_add_i32 m0, s6, 0xe000
	s_nop 0
	global_load_lds_dwordx4 v[252:253], off
	s_cmp_lg_u32 s98, 0
	s_cbranch_scc1 .Lsk1_p13
	s_waitcnt vmcnt(8)
